# speedup vs baseline: 1.0154x; 1.0154x over previous
; DEV void finishSM(f32x16& p0, f32x16& p1, float alpha, float& l_reg, bf16x8& pa0, bf16x8& pa1, bf16x8& pa2, bf16x8& pa3) {
; #pragma unroll
;   for (int r = 0; r < 16; ++r) p1[r] = __builtin_amdgcn_exp2f(p1[r]);
;   float ps = 0;
; #pragma unroll
;   for (int r = 0; r < 16; ++r) ps += p0[r];
; #pragma unroll
;   for (int r = 0; r < 16; ++r) ps += p1[r];
;   { auto rr = __builtin_amdgcn_permlane32_swap(__float_as_uint(ps), __float_as_uint(ps), false, false);
;     ps = __uint_as_float(rr[0]) + __uint_as_float(rr[1]); }
;   l_reg = l_reg * alpha + ps;
;     ...
;   PK4(p0, 0, pa0); PK4(p0, 8, pa1); PK4(p1, 0, pa2); PK4(p1, 8, pa3);
; DEV void qkt(f32x16& p0, f32x16& p1, const char* Ks, const char* KPs, const bf16x8* qr, const char* qpl, int r32, int hi) {
;   p0 = f32x16{}; p1 = f32x16{};
; #pragma unroll
;   for (int d0 = 0; d0 < 8; ++d0) { int cb = (d0 * 16 + hi * 8) * 2;
;     bf16x8 b0 = *reinterpret_cast<const bf16x8*>(Ks + KSWZ(r32, cb));
;     bf16x8 b1 = *reinterpret_cast<const bf16x8*>(Ks + KSWZ(32 + r32, cb));
;     bf16x8 qq = d0 < NQR ? qr[d0 < NQR ? d0 : 0] : *reinterpret_cast<const bf16x8*>(qpl + (d0 - NQR) * 1024);
;     p0 = __builtin_amdgcn_mfma_f32_32x32x16_bf16(b0, qq, p0, 0, 0, 0);
;     p1 = __builtin_amdgcn_mfma_f32_32x32x16_bf16(b1, qq, p1, 0, 0, 0); }
; #pragma unroll
;   for (int d1 = 0; d1 < 4; ++d1) { int cb = (d1 * 16 + hi * 8) * 2;
;     bf16x8 b0 = *reinterpret_cast<const bf16x8*>(KPs + KPSWZ(r32, cb));
;     bf16x8 b1 = *reinterpret_cast<const bf16x8*>(KPs + KPSWZ(32 + r32, cb));
;     bf16x8 qp = *reinterpret_cast<const bf16x8*>(qpl + (8 - NQR + d1) * 1024);
;     p0 = __builtin_amdgcn_mfma_f32_32x32x16_bf16(b0, qp, p0, 0, 0, 0);
;     p1 = __builtin_amdgcn_mfma_f32_32x32x16_bf16(b1, qp, p1, 0, 0, 0); }
; }
.LBB0_304:
	s_barrier
	ds_read_b128 v[64:67], v159 offset:49152
	ds_read_b128 v[68:71], v159 offset:57344
	ds_read_b128 v[188:191], v162 offset:49152
	ds_read_b128 v[202:205], v162 offset:57344
	s_waitcnt vmcnt(0)
	ds_write_b128 v154, v[238:241] offset:16384
	ds_write_b128 v155, v[242:245] offset:16384
	s_mov_b32 s0, 0x40000
	v_add_co_u32_e32 v224, vcc, s0, v142
	s_nop 1
	v_addc_co_u32_e32 v225, vcc, 0, v143, vcc
	global_load_dwordx4 v[226:229], v[142:143], off
	global_load_dwordx4 v[230:233], v[224:225], off
	global_load_dwordx4 v[234:237], v[140:141], off
	global_load_dwordx4 v[238:241], v[142:143], off offset:256
	global_load_dwordx4 v[242:245], v[224:225], off offset:256
	v_add_f32_e32 v133, 0, v196
	v_add_f32_e32 v133, v199, v133
	s_waitcnt lgkmcnt(5)
	v_mfma_f32_32x32x16_bf16 v[80:95], v[64:67], v[108:111], 0
	v_add_f32_e32 v133, v197, v133
	v_add_f32_e32 v133, v200, v133
	v_add_f32_e32 v133, v198, v133
	v_add_f32_e32 v133, v201, v133
	v_add_f32_e32 v133, v194, v133
	v_add_f32_e32 v133, v195, v133
	v_add_f32_e32 v133, v134, v133
	s_waitcnt lgkmcnt(4)
	v_mfma_f32_32x32x16_bf16 v[64:79], v[68:71], v[108:111], 0
	v_add_f32_e32 v133, v192, v133
	v_add_f32_e32 v133, v135, v133
	v_add_f32_e32 v133, v193, v133
	v_exp_f32_e32 v126, v126
	v_add_f32_e32 v133, v128, v133
	v_exp_f32_e32 v127, v127
	v_add_f32_e32 v133, v130, v133
	s_waitcnt lgkmcnt(0)
	v_mfma_f32_32x32x16_bf16 v[64:79], v[202:205], v[104:107], v[64:79]
	v_exp_f32_e32 v124, v124
	v_add_f32_e32 v133, v129, v133
	v_exp_f32_e32 v125, v125
	v_add_f32_e32 v133, v131, v133
	v_or_b32_e32 v187, 0x12000, v175
	v_exp_f32_e32 v120, v120
	v_add_f32_e32 v133, v126, v133
	v_mfma_f32_32x32x16_bf16 v[80:95], v[188:191], v[104:107], v[80:95]
	ds_read_b128 v[188:191], v163 offset:49152
	ds_read_b128 v[202:205], v163 offset:57344
	v_exp_f32_e32 v121, v121
	v_add_f32_e32 v133, v127, v133
	v_exp_f32_e32 v116, v116
	v_add_f32_e32 v133, v124, v133
	v_exp_f32_e32 v117, v117
	v_add_f32_e32 v133, v125, v133
	s_waitcnt lgkmcnt(0)
	v_mfma_f32_32x32x16_bf16 v[64:79], v[202:205], v[100:103], v[64:79]
	v_exp_f32_e32 v112, v112
	v_add_f32_e32 v133, v120, v133
	v_exp_f32_e32 v113, v113
	v_add_f32_e32 v133, v121, v133
	v_exp_f32_e32 v122, v122
	v_add_f32_e32 v133, v116, v133
	v_exp_f32_e32 v123, v123
	v_mfma_f32_32x32x16_bf16 v[80:95], v[188:191], v[100:103], v[80:95]
	ds_read_b128 v[188:191], v166 offset:49152
	ds_read_b128 v[202:205], v166 offset:57344
	v_add_f32_e32 v133, v117, v133
	v_exp_f32_e32 v118, v118
	v_add_f32_e32 v133, v112, v133
	v_exp_f32_e32 v119, v119
	v_add_f32_e32 v133, v113, v133
	v_exp_f32_e32 v114, v114
	s_waitcnt lgkmcnt(0)
	v_mfma_f32_32x32x16_bf16 v[64:79], v[202:205], v[96:99], v[64:79]
	v_add_f32_e32 v133, v122, v133
	v_exp_f32_e32 v115, v115
	v_add_f32_e32 v133, v123, v133
	v_add_f32_e32 v133, v118, v133
	v_add_f32_e32 v133, v119, v133
	v_add_f32_e32 v133, v114, v133
	v_mfma_f32_32x32x16_bf16 v[80:95], v[188:191], v[96:99], v[80:95]
	ds_read_b128 v[188:191], v167 offset:49152
	ds_read_b128 v[202:205], v167 offset:57344
	ds_read_b128 v[206:209], v177
	s_waitcnt lgkmcnt(0)
	v_mfma_f32_32x32x16_bf16 v[64:79], v[202:205], v[206:209], v[64:79]
	v_mfma_f32_32x32x16_bf16 v[80:95], v[188:191], v[206:209], v[80:95]
	ds_read_b128 v[188:191], v168 offset:49152
	ds_read_b128 v[202:205], v168 offset:57344
	ds_read_b128 v[206:209], v177 offset:1024
	s_waitcnt lgkmcnt(0)
	v_mfma_f32_32x32x16_bf16 v[64:79], v[202:205], v[206:209], v[64:79]
	v_mfma_f32_32x32x16_bf16 v[80:95], v[188:191], v[206:209], v[80:95]
	ds_read_b128 v[188:191], v160 offset:49152
	ds_read_b128 v[202:205], v160 offset:57344
	ds_read_b128 v[206:209], v177 offset:2048
	s_waitcnt lgkmcnt(0)
	v_mfma_f32_32x32x16_bf16 v[64:79], v[202:205], v[206:209], v[64:79]
	v_mfma_f32_32x32x16_bf16 v[80:95], v[188:191], v[206:209], v[80:95]
	ds_read_b128 v[188:191], v161 offset:49152
	ds_read_b128 v[202:205], v161 offset:57344
	ds_read_b128 v[206:209], v177 offset:3072
	s_waitcnt lgkmcnt(0)
	v_mfma_f32_32x32x16_bf16 v[64:79], v[202:205], v[206:209], v[64:79]
	v_mfma_f32_32x32x16_bf16 v[80:95], v[188:191], v[206:209], v[80:95]
	ds_read_b128 v[188:191], v184
	ds_read_b128 v[202:205], v185
	ds_read_b128 v[206:209], v177 offset:4096
	s_waitcnt lgkmcnt(0)
	v_mfma_f32_32x32x16_bf16 v[64:79], v[202:205], v[206:209], v[64:79]
	v_mfma_f32_32x32x16_bf16 v[80:95], v[188:191], v[206:209], v[80:95]
	ds_read_b128 v[188:191], v181
	ds_read_b128 v[202:205], v182
	ds_read_b128 v[206:209], v177 offset:5120
	s_waitcnt lgkmcnt(0)
	v_mfma_f32_32x32x16_bf16 v[64:79], v[202:205], v[206:209], v[64:79]
	v_mfma_f32_32x32x16_bf16 v[80:95], v[188:191], v[206:209], v[80:95]
	ds_read_b128 v[188:191], v179
	ds_read_b128 v[202:205], v180
	ds_read_b128 v[206:209], v177 offset:6144
	s_waitcnt lgkmcnt(0)
	v_mfma_f32_32x32x16_bf16 v[64:79], v[202:205], v[206:209], v[64:79]
	ds_read_b128 v[202:205], v187
	v_mfma_f32_32x32x16_bf16 v[80:95], v[188:191], v[206:209], v[80:95]
	v_or_b32_e32 v188, 0x13000, v175
	ds_read_b128 v[206:209], v188
	ds_read_b128 v[210:213], v177 offset:7168
	v_add_f32_e32 v189, v115, v133
	v_mov_b32_e32 v190, v189
	s_nop 1
	v_permlane32_swap_b32_e32 v189, v190
	v_cvt_pk_bf16_f32 v196, v196, v199
	s_waitcnt lgkmcnt(0)
; DEV void partialSM(f32x16& p0, f32x16& p1, float& m_reg, float& mn, float& alpha) {
;   constexpr float C = SCALE * 1.4426950408889634f;
;   float pmax = p0[0];
; #pragma unroll
;   for (int r = 1; r < 16; ++r) pmax = fmaxf(pmax, p0[r]);
; #pragma unroll
;   for (int r = 0; r < 16; ++r) pmax = fmaxf(pmax, p1[r]);
;   { auto rr = __builtin_amdgcn_permlane32_swap(__float_as_uint(pmax), __float_as_uint(pmax), false, false);
;     pmax = fmaxf(__uint_as_float(rr[0]), __uint_as_float(rr[1])); }
;   if (__builtin_expect(__all(pmax - m_reg <= THR / SCALE), 1)) { mn = m_reg; alpha = 1.f; }
;   else { mn = fmaxf(m_reg, pmax); alpha = __builtin_amdgcn_exp2f((m_reg - mn) * C); m_reg = mn; }
;   float mnC = -mn * C;
; #pragma unroll
;   for (int r = 0; r < 16; ++r) p0[r] = fmaf(p0[r], C, mnC);
; #pragma unroll
;   for (int r = 0; r < 16; ++r) p1[r] = fmaf(p1[r], C, mnC);
; #pragma unroll
;   for (int r = 0; r < 16; ++r) p0[r] = __builtin_amdgcn_exp2f(p0[r]);
; }
; DEV void finishSM(f32x16& p0, f32x16& p1, float alpha, float& l_reg, bf16x8& pa0, bf16x8& pa1, bf16x8& pa2, bf16x8& pa3) {
; #pragma unroll
;   for (int r = 0; r < 16; ++r) p1[r] = __builtin_amdgcn_exp2f(p1[r]);
;   float ps = 0;
; #pragma unroll
;   for (int r = 0; r < 16; ++r) ps += p0[r];
; #pragma unroll
;   for (int r = 0; r < 16; ++r) ps += p1[r];
;   { auto rr = __builtin_amdgcn_permlane32_swap(__float_as_uint(ps), __float_as_uint(ps), false, false);
;     ps = __uint_as_float(rr[0]) + __uint_as_float(rr[1]); }
;   l_reg = l_reg * alpha + ps;
;     ...
;   PK4(p0, 0, pa0); PK4(p0, 8, pa1); PK4(p1, 0, pa2); PK4(p1, 8, pa3);
;     ...
; }
; template <int OFF> DEV s16x4 tr_read(int vb) {
;   s16x4 r; asm volatile("ds_read_b64_tr_b16 %0, %1 offset:%2" : "=&v"(r) : "v"(vb), "i"(OFF) : "memory"); return r;
; }
; template <int D0> DEV void pv_one(f32x16& od, int vb, bf16x8 pa0, bf16x8 pa1, bf16x8 pa2, bf16x8 pa3) {
;   const s16x4 l0 = tr_read<v_rd_off(D0, 0, 0)>(vb), h0 = tr_read<v_rd_off(D0, 0, 1)>(vb), l1 = tr_read<v_rd_off(D0, 1, 0)>(vb), h1 = tr_read<v_rd_off(D0, 1, 1)>(vb);
;   const s16x4 l2 = tr_read<v_rd_off(D0, 2, 0)>(vb), h2 = tr_read<v_rd_off(D0, 2, 1)>(vb), l3 = tr_read<v_rd_off(D0, 3, 0)>(vb), h3 = tr_read<v_rd_off(D0, 3, 1)>(vb);
;   asm volatile("s_waitcnt lgkmcnt(0)" ::: "memory"); SBAR();
;     ...
;   od = __builtin_amdgcn_mfma_f32_32x32x16_bf16(pa0, PK(l0, h0), od, 0, 0, 0);
	v_mfma_f32_32x32x16_bf16 v[80:95], v[202:205], v[210:213], v[80:95]
	v_cvt_pk_bf16_f32 v197, v197, v200
	v_cvt_pk_bf16_f32 v198, v198, v201
	v_cvt_pk_bf16_f32 v199, v194, v195
	v_cvt_pk_bf16_f32 v192, v134, v192
	v_cvt_pk_bf16_f32 v193, v135, v193
	v_cvt_pk_bf16_f32 v194, v128, v130
	v_cvt_pk_bf16_f32 v195, v129, v131
	v_mfma_f32_32x32x16_bf16 v[64:79], v[206:209], v[210:213], v[64:79]
	v_cvt_pk_bf16_f32 v200, v126, v127
	v_cvt_pk_bf16_f32 v201, v124, v125
	v_cvt_pk_bf16_f32 v202, v120, v121
	v_cvt_pk_bf16_f32 v203, v116, v117
	v_cvt_pk_bf16_f32 v204, v112, v113
	v_cvt_pk_bf16_f32 v205, v122, v123
	v_cvt_pk_bf16_f32 v206, v118, v119
	v_cvt_pk_bf16_f32 v207, v114, v115
	v_permlane32_swap_b32_e32 v196, v198
	v_permlane32_swap_b32_e32 v197, v199
	v_permlane32_swap_b32_e32 v192, v194
	v_permlane32_swap_b32_e32 v193, v195
	v_permlane32_swap_b32_e32 v200, v202
	v_permlane32_swap_b32_e32 v201, v203
	v_permlane32_swap_b32_e32 v204, v206
	v_permlane32_swap_b32_e32 v205, v207
	s_waitcnt vmcnt(2)
	ds_write_b128 v156, v[226:229] offset:32768
	ds_write_b128 v157, v[230:233] offset:32768
	ds_write_b128 v158, v[234:237]
	ds_read_b64_tr_b16 v[208:209], v153 offset:0
	ds_read_b64_tr_b16 v[210:211], v153 offset:0x800
	ds_read_b64_tr_b16 v[212:213], v153 offset:0x1000
	ds_read_b64_tr_b16 v[214:215], v153 offset:0x1800
	ds_read_b64_tr_b16 v[216:217], v153 offset:0x2000
	ds_read_b64_tr_b16 v[218:219], v153 offset:0x2800
	ds_read_b64_tr_b16 v[220:221], v153 offset:0x3000
	ds_read_b64_tr_b16 v[222:223], v153 offset:0x3800
	s_waitcnt lgkmcnt(6)
	s_nop 0
	v_mfma_f32_32x32x16_bf16 v[0:15], v[196:199], v[208:211], v[0:15]
	ds_read_b64_tr_b16 v[208:209], v153 offset:0x200
	ds_read_b64_tr_b16 v[210:211], v153 offset:0xa00
	v_max_f32_e32 v133, v81, v81
	v_max_f32_e32 v134, v80, v80
	v_max_f32_e32 v133, v134, v133
	v_max3_f32 v133, v133, v82, v83
	v_max3_f32 v133, v133, v84, v85
	s_waitcnt lgkmcnt(6)
	v_mfma_f32_32x32x16_bf16 v[0:15], v[192:195], v[212:215], v[0:15]
	ds_read_b64_tr_b16 v[212:213], v153 offset:0x1200
	ds_read_b64_tr_b16 v[214:215], v153 offset:0x1a00
	v_max3_f32 v133, v133, v86, v87
	v_max3_f32 v133, v133, v88, v89
	v_max3_f32 v133, v133, v90, v91
	v_max3_f32 v133, v133, v92, v93
	v_max3_f32 v133, v133, v94, v95
	s_waitcnt lgkmcnt(6)
	v_mfma_f32_32x32x16_bf16 v[0:15], v[200:203], v[216:219], v[0:15]
	ds_read_b64_tr_b16 v[216:217], v153 offset:0x2200
	ds_read_b64_tr_b16 v[218:219], v153 offset:0x2a00
	v_max3_f32 v133, v133, v64, v65
	v_max3_f32 v133, v133, v66, v67
	v_max3_f32 v133, v133, v68, v69
	v_max3_f32 v133, v133, v70, v71
	v_max3_f32 v133, v133, v72, v73
	s_waitcnt lgkmcnt(6)
	v_mfma_f32_32x32x16_bf16 v[0:15], v[204:207], v[220:223], v[0:15]
	ds_read_b64_tr_b16 v[220:221], v153 offset:0x3200
	ds_read_b64_tr_b16 v[222:223], v153 offset:0x3a00
	v_max3_f32 v133, v133, v74, v75
	v_max3_f32 v133, v133, v76, v77
	v_max3_f32 v133, v133, v78, v79
	v_mov_b32_e32 v134, v133
	s_waitcnt lgkmcnt(6)
	v_mfma_f32_32x32x16_bf16 v[48:63], v[196:199], v[208:211], v[48:63]
	ds_read_b64_tr_b16 v[208:209], v153 offset:0x400
	ds_read_b64_tr_b16 v[210:211], v153 offset:0xc00
	s_nop 1
	v_permlane32_swap_b32_e32 v133, v134
	v_max_f32_e32 v134, v134, v134
	v_max_f32_e32 v133, v133, v133
	s_waitcnt lgkmcnt(6)
	v_mfma_f32_32x32x16_bf16 v[48:63], v[192:195], v[212:215], v[48:63]
	ds_read_b64_tr_b16 v[212:213], v153 offset:0x1400
	ds_read_b64_tr_b16 v[214:215], v153 offset:0x1c00
	v_max_f32_e32 v133, v133, v134
	v_sub_f32_e32 v134, v133, v132
	v_cmp_ge_f32_e32 vcc, s72, v134
	v_max_f32_e32 v134, v132, v132
	s_waitcnt lgkmcnt(6)
	v_mfma_f32_32x32x16_bf16 v[48:63], v[200:203], v[216:219], v[48:63]
	ds_read_b64_tr_b16 v[216:217], v153 offset:0x2400
	ds_read_b64_tr_b16 v[218:219], v153 offset:0x2c00
	v_max_f32_e32 v133, v134, v133
	v_sub_f32_e32 v134, v132, v133
	v_mul_f32_e32 v134, 0x3dd53b94, v134
	v_exp_f32_e32 v134, v134
	s_waitcnt lgkmcnt(6)
	v_mfma_f32_32x32x16_bf16 v[48:63], v[204:207], v[220:223], v[48:63]
	ds_read_b64_tr_b16 v[220:221], v153 offset:0x3400
	ds_read_b64_tr_b16 v[222:223], v153 offset:0x3c00
	s_cmp_eq_u64 vcc, exec
	s_cselect_b64 s[4:5], -1, 0
	v_cndmask_b32_e64 v226, v133, v132, s[4:5]
	v_mul_f32_e32 v227, 0xbdd53b94, v226
	s_waitcnt lgkmcnt(6)
	v_mfma_f32_32x32x16_bf16 v[32:47], v[196:199], v[208:211], v[32:47]
	ds_read_b64_tr_b16 v[208:209], v153 offset:0x600
	ds_read_b64_tr_b16 v[210:211], v153 offset:0xe00
	v_fmamk_f32 v80, v80, 0x3dd53b94, v227
	v_fmamk_f32 v81, v81, 0x3dd53b94, v227
	v_fmamk_f32 v82, v82, 0x3dd53b94, v227
	v_fmamk_f32 v83, v83, 0x3dd53b94, v227
	s_waitcnt lgkmcnt(6)
	v_mfma_f32_32x32x16_bf16 v[32:47], v[192:195], v[212:215], v[32:47]
	ds_read_b64_tr_b16 v[212:213], v153 offset:0x1600
	ds_read_b64_tr_b16 v[214:215], v153 offset:0x1e00
	v_fmamk_f32 v84, v84, 0x3dd53b94, v227
	v_fmamk_f32 v85, v85, 0x3dd53b94, v227
	v_fmamk_f32 v86, v86, 0x3dd53b94, v227
	v_fmamk_f32 v87, v87, 0x3dd53b94, v227
	s_waitcnt lgkmcnt(6)
	v_mfma_f32_32x32x16_bf16 v[32:47], v[200:203], v[216:219], v[32:47]
	ds_read_b64_tr_b16 v[216:217], v153 offset:0x2600
	ds_read_b64_tr_b16 v[218:219], v153 offset:0x2e00
	v_fmamk_f32 v88, v88, 0x3dd53b94, v227
	v_fmamk_f32 v89, v89, 0x3dd53b94, v227
	v_fmamk_f32 v90, v90, 0x3dd53b94, v227
	v_fmamk_f32 v91, v91, 0x3dd53b94, v227
	s_waitcnt lgkmcnt(6)
	v_mfma_f32_32x32x16_bf16 v[32:47], v[204:207], v[220:223], v[32:47]
	ds_read_b64_tr_b16 v[220:221], v153 offset:0x3600
	ds_read_b64_tr_b16 v[222:223], v153 offset:0x3e00
	v_fmamk_f32 v92, v92, 0x3dd53b94, v227
	v_fmamk_f32 v93, v93, 0x3dd53b94, v227
	v_fmamk_f32 v94, v94, 0x3dd53b94, v227
	v_fmamk_f32 v95, v95, 0x3dd53b94, v227
	s_waitcnt lgkmcnt(6)
	v_mfma_f32_32x32x16_bf16 v[16:31], v[196:199], v[208:211], v[16:31]
	v_exp_f32_e32 v125, v80
	v_exp_f32_e32 v127, v81
	v_exp_f32_e32 v123, v82
	v_exp_f32_e32 v126, v83
	s_waitcnt lgkmcnt(4)
	v_mfma_f32_32x32x16_bf16 v[16:31], v[192:195], v[212:215], v[16:31]
	v_exp_f32_e32 v122, v84
	v_exp_f32_e32 v124, v85
	v_exp_f32_e32 v120, v86
	v_exp_f32_e32 v121, v87
	s_waitcnt lgkmcnt(2)
	v_mfma_f32_32x32x16_bf16 v[16:31], v[200:203], v[216:219], v[16:31]
	v_exp_f32_e32 v117, v88
	v_exp_f32_e32 v119, v89
	v_exp_f32_e32 v116, v90
	v_exp_f32_e32 v118, v91
	s_waitcnt lgkmcnt(0)
	v_mfma_f32_32x32x16_bf16 v[16:31], v[204:207], v[220:223], v[16:31]
	v_exp_f32_e32 v113, v92
	v_exp_f32_e32 v115, v93
	v_exp_f32_e32 v112, v94
	v_exp_f32_e32 v114, v95
	v_cndmask_b32_e64 v191, v134, 1.0, s[4:5]
	v_cmp_gt_f32_e32 vcc, 1.0, v191
	s_cbranch_vccz .LBB0_308
	s_and_saveexec_b64 s[8:9], s[6:7]
	ds_write_b32 v150, v191 offset:128
	s_or_b64 exec, exec, s[8:9]
	s_waitcnt lgkmcnt(0)
	v_add_u32_e32 v228, v139, v136
	ds_read_b128 v[208:211], v228 offset:224
	ds_read_b128 v[212:215], v228 offset:192
	ds_read_b128 v[216:219], v228 offset:160
	ds_read_b128 v[220:223], v228 offset:128
	s_waitcnt lgkmcnt(3)
	v_pk_mul_f32 v[12:13], v[12:13], v[208:209]
	s_waitcnt lgkmcnt(2)
	v_pk_mul_f32 v[8:9], v[8:9], v[212:213]
	s_waitcnt lgkmcnt(1)
	v_pk_mul_f32 v[4:5], v[4:5], v[216:217]
	v_pk_mul_f32 v[14:15], v[14:15], v[210:211]
	v_pk_mul_f32 v[10:11], v[10:11], v[214:215]
	v_pk_mul_f32 v[6:7], v[6:7], v[218:219]
	s_waitcnt lgkmcnt(0)
	v_pk_mul_f32 v[2:3], v[2:3], v[222:223]
	v_pk_mul_f32 v[0:1], v[0:1], v[220:221]
	v_pk_mul_f32 v[60:61], v[60:61], v[208:209]
	v_pk_mul_f32 v[56:57], v[56:57], v[212:213]
	v_pk_mul_f32 v[52:53], v[52:53], v[216:217]
	v_pk_mul_f32 v[62:63], v[62:63], v[210:211]
	v_pk_mul_f32 v[58:59], v[58:59], v[214:215]
	v_pk_mul_f32 v[54:55], v[54:55], v[218:219]
	v_pk_mul_f32 v[50:51], v[50:51], v[222:223]
	v_pk_mul_f32 v[48:49], v[48:49], v[220:221]
	v_pk_mul_f32 v[44:45], v[44:45], v[208:209]
	v_pk_mul_f32 v[40:41], v[40:41], v[212:213]
	v_pk_mul_f32 v[36:37], v[36:37], v[216:217]
	v_pk_mul_f32 v[46:47], v[46:47], v[210:211]
	v_pk_mul_f32 v[42:43], v[42:43], v[214:215]
	v_pk_mul_f32 v[38:39], v[38:39], v[218:219]
	v_pk_mul_f32 v[34:35], v[34:35], v[222:223]
	v_pk_mul_f32 v[32:33], v[32:33], v[220:221]
	v_pk_mul_f32 v[28:29], v[28:29], v[208:209]
	v_pk_mul_f32 v[24:25], v[24:25], v[212:213]
	v_pk_mul_f32 v[20:21], v[20:21], v[216:217]
	v_pk_mul_f32 v[30:31], v[30:31], v[210:211]
	v_pk_mul_f32 v[26:27], v[26:27], v[214:215]
	v_pk_mul_f32 v[22:23], v[22:23], v[218:219]
	v_pk_mul_f32 v[18:19], v[18:19], v[222:223]
	v_pk_mul_f32 v[16:17], v[16:17], v[220:221]

; DEV void partialSM(f32x16& p0, f32x16& p1, float& m_reg, float& mn, float& alpha) {
;     ...
;   if (__builtin_expect(__all(pmax - m_reg <= THR / SCALE), 1)) { mn = m_reg; alpha = 1.f; }
;   else { mn = fmaxf(m_reg, pmax); alpha = __builtin_amdgcn_exp2f((m_reg - mn) * C); m_reg = mn; }
;   float mnC = -mn * C;
; #pragma unroll
;   for (int r = 0; r < 16; ++r) p0[r] = fmaf(p0[r], C, mnC);
; #pragma unroll
;   for (int r = 0; r < 16; ++r) p1[r] = fmaf(p1[r], C, mnC);
; #pragma unroll
;   for (int r = 0; r < 16; ++r) p0[r] = __builtin_amdgcn_exp2f(p0[r]);
; }
; DEV void qkt(f32x16& p0, f32x16& p1, const char* Ks, const char* KPs, const bf16x8* qr, const char* qpl, int r32, int hi) {
;   p0 = f32x16{}; p1 = f32x16{};
; #pragma unroll
;   for (int d0 = 0; d0 < 8; ++d0) { int cb = (d0 * 16 + hi * 8) * 2;
;     bf16x8 b0 = *reinterpret_cast<const bf16x8*>(Ks + KSWZ(r32, cb));
;     bf16x8 b1 = *reinterpret_cast<const bf16x8*>(Ks + KSWZ(32 + r32, cb));
;     bf16x8 qq = d0 < NQR ? qr[d0 < NQR ? d0 : 0] : *reinterpret_cast<const bf16x8*>(qpl + (d0 - NQR) * 1024);
;     p0 = __builtin_amdgcn_mfma_f32_32x32x16_bf16(b0, qq, p0, 0, 0, 0);
;     p1 = __builtin_amdgcn_mfma_f32_32x32x16_bf16(b1, qq, p1, 0, 0, 0); }
; #pragma unroll
;   for (int d1 = 0; d1 < 4; ++d1) { int cb = (d1 * 16 + hi * 8) * 2;
;     bf16x8 b0 = *reinterpret_cast<const bf16x8*>(KPs + KPSWZ(r32, cb));
;     bf16x8 b1 = *reinterpret_cast<const bf16x8*>(KPs + KPSWZ(32 + r32, cb));
;     bf16x8 qp = *reinterpret_cast<const bf16x8*>(qpl + (8 - NQR + d1) * 1024);
;     p0 = __builtin_amdgcn_mfma_f32_32x32x16_bf16(b0, qp, p0, 0, 0, 0);
;     p1 = __builtin_amdgcn_mfma_f32_32x32x16_bf16(b1, qp, p1, 0, 0, 0); }
.LBB0_312:
	v_cndmask_b32_e64 v132, v132, v192, s[4:5]
	v_mul_f32_e32 v114, 0xbdd53b94, v132
	v_mov_b32_e32 v115, v114
	v_fmamk_f32 v80, v80, 0x3dd53b94, v114
	v_fmamk_f32 v81, v81, 0x3dd53b94, v114
	v_fmamk_f32 v82, v82, 0x3dd53b94, v114
	v_fmamk_f32 v83, v83, 0x3dd53b94, v114
	v_fmamk_f32 v84, v84, 0x3dd53b94, v114
	v_fmamk_f32 v85, v85, 0x3dd53b94, v114
	v_fmamk_f32 v86, v86, 0x3dd53b94, v114
	v_fmamk_f32 v87, v87, 0x3dd53b94, v114
	v_fmamk_f32 v88, v88, 0x3dd53b94, v114
	v_fmamk_f32 v89, v89, 0x3dd53b94, v114
	v_fmamk_f32 v90, v90, 0x3dd53b94, v114
	v_fmamk_f32 v91, v91, 0x3dd53b94, v114
	v_fmamk_f32 v92, v92, 0x3dd53b94, v114
	v_fmamk_f32 v93, v93, 0x3dd53b94, v114
	v_fmamk_f32 v94, v94, 0x3dd53b94, v114
	v_fmac_f32_e32 v115, 0x3dd53b94, v95
	v_exp_f32_e32 v196, v80
	v_exp_f32_e32 v199, v81
	v_exp_f32_e32 v197, v82
	v_exp_f32_e32 v200, v83
	v_exp_f32_e32 v198, v84
	v_exp_f32_e32 v201, v85
	v_exp_f32_e32 v194, v86
	v_exp_f32_e32 v195, v87
	v_exp_f32_e32 v134, v88
	v_exp_f32_e32 v192, v89
	v_exp_f32_e32 v135, v90
	v_exp_f32_e32 v193, v91
	v_exp_f32_e32 v128, v92
	v_exp_f32_e32 v130, v93
	v_exp_f32_e32 v129, v94
	v_exp_f32_e32 v131, v115
	v_pk_fma_f32 v[126:127], v[64:65], s[30:31], v[114:115] op_sel_hi:[1,0,0]
	v_add_f32_e32 v64, v189, v190
	s_mov_b64 s[0:1], 0x44000
	v_fmac_f32_e32 v64, v186, v151
	v_add_f32_e32 v151, v202, v203
	v_lshl_add_u64 v[140:141], v[140:141], 0, s[0:1]
	s_add_i32 s78, s78, 2
	s_mov_b64 s[0:1], 0x100000
	v_pk_fma_f32 v[124:125], v[66:67], s[30:31], v[114:115] op_sel_hi:[1,0,0]
	v_pk_fma_f32 v[120:121], v[68:69], s[30:31], v[114:115] op_sel_hi:[1,0,0]
	v_pk_fma_f32 v[116:117], v[70:71], s[30:31], v[114:115] op_sel_hi:[1,0,0]
	v_pk_fma_f32 v[112:113], v[72:73], s[30:31], v[114:115] op_sel_hi:[1,0,0]
	v_pk_fma_f32 v[122:123], v[74:75], s[30:31], v[114:115] op_sel_hi:[1,0,0]
	v_pk_fma_f32 v[118:119], v[76:77], s[30:31], v[114:115] op_sel_hi:[1,0,0]
	v_pk_fma_f32 v[114:115], v[78:79], s[30:31], v[114:115] op_sel_hi:[1,0,0]
	v_fmac_f32_e32 v151, v64, v191
	s_cmp_ge_u32 s78, s77
	v_lshl_add_u64 v[142:143], v[142:143], 0, s[0:1]
	v_mov_b32_e32 v186, v133
	s_waitcnt lgkmcnt(0)
	s_cbranch_scc1 .Lattn_exit
	s_branch .LBB0_304
.Lattn_exit:
	s_barrier
.LBB0_314:
	s_waitcnt vmcnt(0)
	ds_write_b128 v154, v[238:241] offset:16384
	ds_write_b128 v155, v[242:245] offset:16384
	ds_read_b128 v[64:67], v159 offset:49152
	ds_read_b128 v[68:71], v159 offset:57344
	v_exp_f32_e32 v116, v116
	v_exp_f32_e32 v117, v117
	v_exp_f32_e32 v112, v112
	s_waitcnt lgkmcnt(1)
	v_mfma_f32_32x32x16_bf16 v[80:95], v[64:67], v[108:111], 0
	v_exp_f32_e32 v113, v113
	v_exp_f32_e32 v118, v118
	v_exp_f32_e32 v119, v119
	v_exp_f32_e32 v114, v114
	v_exp_f32_e32 v115, v115
	s_waitcnt lgkmcnt(0)
	v_mfma_f32_32x32x16_bf16 v[64:79], v[68:71], v[108:111], 0
	ds_read_b128 v[108:111], v162 offset:49152
	ds_read_b128 v[140:143], v162 offset:57344
	s_waitcnt lgkmcnt(1)
	v_mfma_f32_32x32x16_bf16 v[80:95], v[108:111], v[104:107], v[80:95]
	s_waitcnt lgkmcnt(0)
	v_mfma_f32_32x32x16_bf16 v[64:79], v[140:143], v[104:107], v[64:79]
	ds_read_b128 v[104:107], v163 offset:49152
	ds_read_b128 v[108:111], v163 offset:57344
	s_waitcnt lgkmcnt(1)
	v_mfma_f32_32x32x16_bf16 v[80:95], v[104:107], v[100:103], v[80:95]
	s_waitcnt lgkmcnt(0)
	v_mfma_f32_32x32x16_bf16 v[64:79], v[108:111], v[100:103], v[64:79]
	ds_read_b128 v[100:103], v166 offset:49152
	ds_read_b128 v[104:107], v166 offset:57344
	v_exp_f32_e32 v108, v124
	v_exp_f32_e32 v109, v125
	v_exp_f32_e32 v110, v120
	v_exp_f32_e32 v111, v121
	v_exp_f32_e32 v120, v122
	v_exp_f32_e32 v121, v123
	s_waitcnt lgkmcnt(1)
	v_mfma_f32_32x32x16_bf16 v[80:95], v[100:103], v[96:99], v[80:95]
	s_waitcnt lgkmcnt(0)
	v_mfma_f32_32x32x16_bf16 v[64:79], v[104:107], v[96:99], v[64:79]
	ds_read_b128 v[96:99], v167 offset:49152
	ds_read_b128 v[100:103], v167 offset:57344
	ds_read_b128 v[104:107], v177
	s_waitcnt lgkmcnt(0)
	v_mfma_f32_32x32x16_bf16 v[80:95], v[96:99], v[104:107], v[80:95]
	v_mfma_f32_32x32x16_bf16 v[64:79], v[100:103], v[104:107], v[64:79]
	ds_read_b128 v[96:99], v168 offset:49152
	ds_read_b128 v[100:103], v168 offset:57344
	ds_read_b128 v[104:107], v177 offset:1024
	s_waitcnt lgkmcnt(0)
	v_mfma_f32_32x32x16_bf16 v[80:95], v[96:99], v[104:107], v[80:95]
	v_mfma_f32_32x32x16_bf16 v[64:79], v[100:103], v[104:107], v[64:79]
	ds_read_b128 v[96:99], v160 offset:49152
	ds_read_b128 v[100:103], v160 offset:57344
	ds_read_b128 v[104:107], v177 offset:2048
	s_waitcnt lgkmcnt(0)
	v_mfma_f32_32x32x16_bf16 v[80:95], v[96:99], v[104:107], v[80:95]
	v_mfma_f32_32x32x16_bf16 v[64:79], v[100:103], v[104:107], v[64:79]
	ds_read_b128 v[96:99], v161 offset:49152
	ds_read_b128 v[100:103], v161 offset:57344
	ds_read_b128 v[104:107], v177 offset:3072
	s_waitcnt lgkmcnt(0)
	v_mfma_f32_32x32x16_bf16 v[80:95], v[96:99], v[104:107], v[80:95]
	v_mfma_f32_32x32x16_bf16 v[64:79], v[100:103], v[104:107], v[64:79]
	ds_read_b128 v[96:99], v184
	ds_read_b128 v[100:103], v185
	ds_read_b128 v[104:107], v177 offset:4096
	s_waitcnt lgkmcnt(0)
	v_mfma_f32_32x32x16_bf16 v[80:95], v[96:99], v[104:107], v[80:95]
	v_mfma_f32_32x32x16_bf16 v[64:79], v[100:103], v[104:107], v[64:79]
	ds_read_b128 v[96:99], v181
	ds_read_b128 v[100:103], v182
	ds_read_b128 v[104:107], v177 offset:5120
	s_waitcnt lgkmcnt(0)
	v_mfma_f32_32x32x16_bf16 v[80:95], v[96:99], v[104:107], v[80:95]
	v_mfma_f32_32x32x16_bf16 v[64:79], v[100:103], v[104:107], v[64:79]
	ds_read_b128 v[96:99], v179
	ds_read_b128 v[100:103], v180
	ds_read_b128 v[104:107], v177 offset:6144
	s_waitcnt lgkmcnt(0)
; DEV void partialSM(f32x16& p0, f32x16& p1, float& m_reg, float& mn, float& alpha) {
;   constexpr float C = SCALE * 1.4426950408889634f;
;   float pmax = p0[0];
; #pragma unroll
;   for (int r = 1; r < 16; ++r) pmax = fmaxf(pmax, p0[r]);
; #pragma unroll
;   for (int r = 0; r < 16; ++r) pmax = fmaxf(pmax, p1[r]);
;   { auto rr = __builtin_amdgcn_permlane32_swap(__float_as_uint(pmax), __float_as_uint(pmax), false, false);
;     pmax = fmaxf(__uint_as_float(rr[0]), __uint_as_float(rr[1])); }
;   if (__builtin_expect(__all(pmax - m_reg <= THR / SCALE), 1)) { mn = m_reg; alpha = 1.f; }
;   else { mn = fmaxf(m_reg, pmax); alpha = __builtin_amdgcn_exp2f((m_reg - mn) * C); m_reg = mn; }
;   float mnC = -mn * C;
; #pragma unroll
;   for (int r = 0; r < 16; ++r) p0[r] = fmaf(p0[r], C, mnC);
; #pragma unroll
;   for (int r = 0; r < 16; ++r) p1[r] = fmaf(p1[r], C, mnC);
; #pragma unroll
;   for (int r = 0; r < 16; ++r) p0[r] = __builtin_amdgcn_exp2f(p0[r]);
; }
; DEV void finishSM(f32x16& p0, f32x16& p1, float alpha, float& l_reg, bf16x8& pa0, bf16x8& pa1, bf16x8& pa2, bf16x8& pa3) {
; #pragma unroll
;   for (int r = 0; r < 16; ++r) p1[r] = __builtin_amdgcn_exp2f(p1[r]);
;   float ps = 0;
; #pragma unroll
;   for (int r = 0; r < 16; ++r) ps += p0[r];
; #pragma unroll
;   for (int r = 0; r < 16; ++r) ps += p1[r];
;   { auto rr = __builtin_amdgcn_permlane32_swap(__float_as_uint(ps), __float_as_uint(ps), false, false);
;     ps = __uint_as_float(rr[0]) + __uint_as_float(rr[1]); }
;   l_reg = l_reg * alpha + ps;
;     ...
;   PK4(p0, 0, pa0); PK4(p0, 8, pa1); PK4(p1, 0, pa2); PK4(p1, 8, pa3);
;     ...
; }
	v_mfma_f32_32x32x16_bf16 v[80:95], v[96:99], v[104:107], v[80:95]
	v_mfma_f32_32x32x16_bf16 v[64:79], v[100:103], v[104:107], v[64:79]
	ds_read_b128 v[96:99], v187
	ds_read_b128 v[100:103], v188
	ds_read_b128 v[104:107], v177 offset:7168
	s_waitcnt lgkmcnt(0)
	v_mfma_f32_32x32x16_bf16 v[80:95], v[96:99], v[104:107], v[80:95]
	v_add_f32_e32 v96, 0, v196
	v_add_f32_e32 v96, v199, v96
	v_add_f32_e32 v96, v197, v96
	v_add_f32_e32 v96, v200, v96
	v_add_f32_e32 v96, v198, v96
	v_add_f32_e32 v96, v201, v96
	v_add_f32_e32 v96, v194, v96
	v_add_f32_e32 v96, v195, v96
	v_add_f32_e32 v96, v134, v96
	v_add_f32_e32 v96, v192, v96
	v_add_f32_e32 v96, v135, v96
	v_add_f32_e32 v96, v193, v96
	v_mfma_f32_32x32x16_bf16 v[64:79], v[100:103], v[104:107], v[64:79]
	v_exp_f32_e32 v106, v126
	v_add_f32_e32 v96, v128, v96
	v_exp_f32_e32 v107, v127
	v_add_f32_e32 v96, v130, v96
	v_add_f32_e32 v96, v129, v96
	v_add_f32_e32 v96, v131, v96
	v_add_f32_e32 v96, v106, v96
	v_add_f32_e32 v96, v107, v96
	v_add_f32_e32 v96, v108, v96
	v_add_f32_e32 v96, v109, v96
	v_add_f32_e32 v96, v110, v96
	v_add_f32_e32 v96, v111, v96
	v_add_f32_e32 v96, v116, v96
	v_add_f32_e32 v96, v117, v96
	v_add_f32_e32 v96, v112, v96
	v_add_f32_e32 v96, v113, v96
	v_add_f32_e32 v96, v120, v96
	v_add_f32_e32 v96, v121, v96
	v_add_f32_e32 v96, v118, v96
	v_add_f32_e32 v96, v119, v96
	v_add_f32_e32 v96, v114, v96
	v_add_f32_e32 v96, v115, v96
	v_mov_b32_e32 v97, v96
	v_cvt_pk_bf16_f32 v98, v196, v199
	v_cvt_pk_bf16_f32 v99, v197, v200
	v_cvt_pk_bf16_f32 v100, v198, v201
	v_cvt_pk_bf16_f32 v101, v194, v195
	s_nop 1
	v_permlane32_swap_b32_e32 v96, v97
	v_permlane32_swap_b32_e32 v98, v100
	v_permlane32_swap_b32_e32 v99, v101
	v_cvt_pk_bf16_f32 v102, v134, v192
	v_cvt_pk_bf16_f32 v103, v135, v193
	v_cvt_pk_bf16_f32 v104, v128, v130
	v_cvt_pk_bf16_f32 v105, v129, v131
	v_cvt_pk_bf16_f32 v106, v106, v107
	v_cvt_pk_bf16_f32 v107, v108, v109
	v_cvt_pk_bf16_f32 v108, v110, v111
	v_cvt_pk_bf16_f32 v109, v116, v117
	v_cvt_pk_bf16_f32 v110, v112, v113
	v_cvt_pk_bf16_f32 v111, v120, v121
	v_cvt_pk_bf16_f32 v112, v118, v119
	v_cvt_pk_bf16_f32 v113, v114, v115
	s_nop 0
	v_permlane32_swap_b32_e32 v102, v104
	v_permlane32_swap_b32_e32 v103, v105
	v_permlane32_swap_b32_e32 v106, v108
	v_permlane32_swap_b32_e32 v107, v109
	v_permlane32_swap_b32_e32 v110, v112
	v_permlane32_swap_b32_e32 v111, v113
	ds_read_b64_tr_b16 v[114:115], v153 offset:0
	ds_read_b64_tr_b16 v[116:117], v153 offset:0x800
	ds_read_b64_tr_b16 v[118:119], v153 offset:0x1000
	ds_read_b64_tr_b16 v[120:121], v153 offset:0x1800
	ds_read_b64_tr_b16 v[122:123], v153 offset:0x2000
	ds_read_b64_tr_b16 v[124:125], v153 offset:0x2800
	ds_read_b64_tr_b16 v[126:127], v153 offset:0x3000
	ds_read_b64_tr_b16 v[128:129], v153 offset:0x3800
	s_waitcnt lgkmcnt(0)
	s_nop 0
	v_mfma_f32_32x32x16_bf16 v[0:15], v[98:101], v[114:117], v[0:15]
	ds_read_b64_tr_b16 v[114:115], v153 offset:0x200
	ds_read_b64_tr_b16 v[116:117], v153 offset:0xa00
	v_mfma_f32_32x32x16_bf16 v[0:15], v[102:105], v[118:121], v[0:15]
	ds_read_b64_tr_b16 v[118:119], v153 offset:0x1200
	ds_read_b64_tr_b16 v[120:121], v153 offset:0x1a00
	v_mfma_f32_32x32x16_bf16 v[0:15], v[106:109], v[122:125], v[0:15]
	ds_read_b64_tr_b16 v[122:123], v153 offset:0x2200
	ds_read_b64_tr_b16 v[124:125], v153 offset:0x2a00
	v_mfma_f32_32x32x16_bf16 v[0:15], v[110:113], v[126:129], v[0:15]
	ds_read_b64_tr_b16 v[126:127], v153 offset:0x3200
	ds_read_b64_tr_b16 v[128:129], v153 offset:0x3a00
	s_waitcnt lgkmcnt(0)
	v_mfma_f32_32x32x16_bf16 v[48:63], v[98:101], v[114:117], v[48:63]
	ds_read_b64_tr_b16 v[114:115], v153 offset:0x400
	ds_read_b64_tr_b16 v[116:117], v153 offset:0xc00
	v_mfma_f32_32x32x16_bf16 v[48:63], v[102:105], v[118:121], v[48:63]
	ds_read_b64_tr_b16 v[118:119], v153 offset:0x1400
	ds_read_b64_tr_b16 v[120:121], v153 offset:0x1c00
	v_mfma_f32_32x32x16_bf16 v[48:63], v[106:109], v[122:125], v[48:63]
	ds_read_b64_tr_b16 v[122:123], v153 offset:0x2400
	ds_read_b64_tr_b16 v[124:125], v153 offset:0x2c00
	v_mfma_f32_32x32x16_bf16 v[48:63], v[110:113], v[126:129], v[48:63]
	ds_read_b64_tr_b16 v[126:127], v153 offset:0x3400
	ds_read_b64_tr_b16 v[128:129], v153 offset:0x3c00
	s_waitcnt lgkmcnt(0)
	v_mfma_f32_32x32x16_bf16 v[32:47], v[98:101], v[114:117], v[32:47]
	ds_read_b64_tr_b16 v[114:115], v153 offset:0x600
	ds_read_b64_tr_b16 v[116:117], v153 offset:0xe00
	v_mfma_f32_32x32x16_bf16 v[32:47], v[102:105], v[118:121], v[32:47]
	ds_read_b64_tr_b16 v[118:119], v153 offset:0x1600
	ds_read_b64_tr_b16 v[120:121], v153 offset:0x1e00
	v_mfma_f32_32x32x16_bf16 v[32:47], v[106:109], v[122:125], v[32:47]
	ds_read_b64_tr_b16 v[122:123], v153 offset:0x2600
	ds_read_b64_tr_b16 v[124:125], v153 offset:0x2e00
	v_mfma_f32_32x32x16_bf16 v[32:47], v[110:113], v[126:129], v[32:47]
	ds_read_b64_tr_b16 v[126:127], v153 offset:0x3600
	ds_read_b64_tr_b16 v[128:129], v153 offset:0x3e00
	s_waitcnt lgkmcnt(0)
	v_mfma_f32_32x32x16_bf16 v[16:31], v[98:101], v[114:117], v[16:31]
	v_max_f32_e32 v98, v81, v81
	v_max_f32_e32 v99, v80, v80
	v_max_f32_e32 v98, v99, v98
	v_max3_f32 v98, v98, v82, v83
	v_max3_f32 v98, v98, v84, v85
	v_max3_f32 v98, v98, v86, v87
	v_max3_f32 v98, v98, v88, v89
	v_max3_f32 v98, v98, v90, v91
	v_max3_f32 v98, v98, v92, v93
	v_mfma_f32_32x32x16_bf16 v[16:31], v[102:105], v[118:121], v[16:31]
	v_max3_f32 v98, v98, v94, v95
	v_max3_f32 v98, v98, v64, v65
	v_max3_f32 v98, v98, v66, v67
	v_max3_f32 v98, v98, v68, v69
	v_max3_f32 v98, v98, v70, v71
	v_max3_f32 v98, v98, v72, v73
	v_max3_f32 v98, v98, v74, v75
	v_max3_f32 v98, v98, v76, v77
	v_mfma_f32_32x32x16_bf16 v[16:31], v[106:109], v[122:125], v[16:31]
	v_max3_f32 v98, v98, v78, v79
	v_mov_b32_e32 v99, v98
	s_nop 1
	v_permlane32_swap_b32_e32 v98, v99
	v_max_f32_e32 v99, v99, v99
	v_max_f32_e32 v98, v98, v98
	v_max_f32_e32 v98, v98, v99
	v_sub_f32_e32 v99, v98, v132
	v_cmp_ge_f32_e32 vcc, s72, v99
	v_max_f32_e32 v99, v132, v132
	v_max_f32_e32 v99, v99, v98
	v_mfma_f32_32x32x16_bf16 v[16:31], v[110:113], v[126:129], v[16:31]
	v_sub_f32_e32 v98, v132, v99
	v_mul_f32_e32 v98, 0x3dd53b94, v98
	v_exp_f32_e32 v98, v98
	s_cmp_eq_u64 vcc, exec
	s_cselect_b64 s[4:5], -1, 0
	v_cndmask_b32_e64 v98, v98, 1.0, s[4:5]
	v_cmp_gt_f32_e32 vcc, 1.0, v98
	s_barrier
	s_cbranch_vccz .LBB0_318
	s_and_saveexec_b64 s[8:9], s[6:7]
	ds_write_b32 v150, v98 offset:128
	s_or_b64 exec, exec, s[8:9]
	s_waitcnt lgkmcnt(0)
	v_add_u32_e32 v112, v139, v136
	ds_read_b128 v[100:103], v112 offset:224
	ds_read_b128 v[104:107], v112 offset:192
	ds_read_b128 v[108:111], v112 offset:160
	ds_read_b128 v[112:115], v112 offset:128
	s_waitcnt lgkmcnt(3)
	v_pk_mul_f32 v[12:13], v[12:13], v[100:101]
	s_waitcnt lgkmcnt(2)
	v_pk_mul_f32 v[8:9], v[8:9], v[104:105]
	s_waitcnt lgkmcnt(1)
	v_pk_mul_f32 v[4:5], v[4:5], v[108:109]
	v_pk_mul_f32 v[14:15], v[14:15], v[102:103]
	v_pk_mul_f32 v[10:11], v[10:11], v[106:107]
	v_pk_mul_f32 v[6:7], v[6:7], v[110:111]
	s_waitcnt lgkmcnt(0)
	v_pk_mul_f32 v[2:3], v[2:3], v[114:115]
	v_pk_mul_f32 v[0:1], v[0:1], v[112:113]
	v_pk_mul_f32 v[60:61], v[60:61], v[100:101]
	v_pk_mul_f32 v[56:57], v[56:57], v[104:105]
	v_pk_mul_f32 v[52:53], v[52:53], v[108:109]
	v_pk_mul_f32 v[62:63], v[62:63], v[102:103]
	v_pk_mul_f32 v[58:59], v[58:59], v[106:107]
	v_pk_mul_f32 v[54:55], v[54:55], v[110:111]
	v_pk_mul_f32 v[50:51], v[50:51], v[114:115]
	v_pk_mul_f32 v[48:49], v[48:49], v[112:113]
	v_pk_mul_f32 v[44:45], v[44:45], v[100:101]
	v_pk_mul_f32 v[40:41], v[40:41], v[104:105]
	v_pk_mul_f32 v[36:37], v[36:37], v[108:109]
	v_pk_mul_f32 v[46:47], v[46:47], v[102:103]
	v_pk_mul_f32 v[42:43], v[42:43], v[106:107]
	v_pk_mul_f32 v[38:39], v[38:39], v[110:111]
	v_pk_mul_f32 v[34:35], v[34:35], v[114:115]
	v_pk_mul_f32 v[32:33], v[32:33], v[112:113]
	v_pk_mul_f32 v[28:29], v[28:29], v[100:101]
	v_pk_mul_f32 v[24:25], v[24:25], v[104:105]
	v_pk_mul_f32 v[20:21], v[20:21], v[108:109]
	v_pk_mul_f32 v[30:31], v[30:31], v[102:103]
	v_pk_mul_f32 v[26:27], v[26:27], v[106:107]
	v_pk_mul_f32 v[22:23], v[22:23], v[110:111]
	v_pk_mul_f32 v[18:19], v[18:19], v[114:115]
	v_pk_mul_f32 v[16:17], v[16:17], v[112:113]
